# v51 + RWKV wave 0: its share of next-next-chunk global loads moved out of the solve interval to the start of the following interval
# baseline (speedup 1.0000x reference)
; __device__ __forceinline__ void rwkv_chunk_item(const P& p, const Ctx& c, int seg, int w, bool save) {
;     ...
;     auto gload = [&](int ch, int tidv) { const int t = tidv >> 5, j0 = (tidv & 31) * 2; const size_t go = ((size_t)b * SEGT + ch * 16 + t) * DMIX + hh * 64 + j0;
;         ga = *(const unsigned*)(SA + go); gb = *(const unsigned*)(SB + go); gk = *(const unsigned*)(SK + go); gr = *(const unsigned*)(SR + go); gv = *(const unsigned*)(SV + go);
;         if (tidv < 64) gg = GTB[((size_t)(b * 32 + ch) * 24 + hh) * 64 + tidv]; };
;     ...
;         if (ch + 2 < SEGT / 16) gload(ch + 2, tidv);
.LBB0_896:
	s_waitcnt lgkmcnt(0)
	s_barrier
	s_andn2_b64 vcc, exec, s[70:71]
	s_cbranch_vccnz .Lrw_dg_skip
	s_cmp_gt_u32 s86, 29
	s_cbranch_scc1 .Lrw_dg_skip
	v_mov_b32_e32 v44, v55
	v_lshlrev_b32_e32 v45, 1, v44
	v_ashrrev_i32_e32 v46, 5, v44
	v_ashrrev_i32_e32 v47, 31, v46
	v_lshl_add_u64 v[46:47], s[76:77], 0, v[46:47]
	v_mov_b64_e32 v[48:49], s[14:15]
	v_mad_u64_u32 v[48:49], s[2:3], v46, s58, v[48:49]
	v_mov_b32_e32 v46, v49
	v_mad_u64_u32 v[46:47], s[2:3], v47, s58, v[46:47]
	v_and_or_b32 v48, v45, 62, v48
	v_mov_b32_e32 v49, v46
	v_lshlrev_b64 v[46:47], 1, v[48:49]
	v_lshl_add_u64 v[48:49], s[16:17], 0, v[46:47]
	global_load_dword v71, v[48:49], off
	v_lshl_add_u64 v[48:49], s[26:27], 0, v[46:47]
	global_load_dword v74, v[48:49], off
	v_lshl_add_u64 v[48:49], s[20:21], 0, v[46:47]
	global_load_dword v75, v[48:49], off
	v_lshl_add_u64 v[48:49], s[30:31], 0, v[46:47]
	v_lshl_add_u64 v[46:47], s[24:25], 0, v[46:47]
	global_load_dword v76, v[48:49], off
	global_load_dword v79, v[46:47], off
	v_cmp_gt_i32_e32 vcc, 64, v44
	s_and_saveexec_b64 s[2:3], vcc
	s_cbranch_execz .Lrw_dg_end
	s_add_i32 s78, s85, s86
	s_mul_hi_i32 s79, s78, 24
	s_mul_i32 s78, s78, 24
	s_add_u32 s78, s78, s46
	s_addc_u32 s79, s79, s47
	s_lshl_b64 s[78:79], s[78:79], 8
	s_add_u32 s78, s81, s78
	v_ashrrev_i32_e32 v45, 31, v44
	s_addc_u32 s79, s82, s79
	v_lshl_add_u64 v[44:45], v[44:45], 2, s[78:79]
	global_load_dword v27, v[44:45], off

; #define LAS __attribute__((address_space(3)))
; __device__ __forceinline__ f32x4 mfma16(bf16x8 a, bf16x8 b, f32x4 c) { return __builtin_amdgcn_mfma_f32_16x16x32_bf16(a, b, c, 0, 0, 0); }
; __device__ __forceinline__ void rwkv_chunk_item(const P& p, const Ctx& c, int seg, int w, bool save) {
;     ...
;     auto eload = [&](int ch) { const size_t rr = (size_t)b * SEGT + ch * 16 + et;
;         e_g = *(const u32x2*)(SG + rr * DMIX + ech); e_v = *(const u32x2*)(SV + rr * DMIX + ech); e_z = *(const u32x2*)(P2 + rr * P2W + 512 + ech); e_rkr = BRKR[(rr * 24 + hh) * 4 + 2]; };
;     ...
;         if (c.wv >= 4) {
;             Zt = mfma16(*(const LAS bf16x8*)(UV + (mtq * 16 + l15) * 40 + quad * 8), *(const LAS bf16x8*)(NT + l15 * 40 + quad * 8), Zt);
;             *(LAS f32x4*)(YB + l15 * 68 + mtq * 16 + quad * 4) = Zt;
;         } else eload(ch);
.Lrw_dg_skip:
	s_mov_b64 s[2:3], -1
	s_and_b64 vcc, exec, s[68:69]
	v_lshlrev_b32_e32 v52, 3, v83
	s_cbranch_vccz .LBB0_898
	v_lshl_add_u64 v[44:45], v[36:37], 0, s[12:13]
	v_add_co_u32_e32 v46, vcc, 0xe900000, v44
	s_mov_b64 s[2:3], 0
	s_nop 0
	v_addc_co_u32_e32 v47, vcc, 0, v45, vcc
	v_add_co_u32_e32 v44, vcc, 0xdd00000, v44
	s_nop 1
	v_addc_co_u32_e32 v45, vcc, 0, v45, vcc
	global_load_dwordx2 v[50:51], v[46:47], off
	global_load_dwordx2 v[48:49], v[44:45], off
	v_lshl_add_u64 v[44:45], v[34:35], 0, s[12:13]
	global_load_dwordx2 v[46:47], v[44:45], off
	v_lshl_add_u64 v[44:45], v[32:33], 0, s[12:13]
	global_load_dword v44, v[44:45], off
	v_lshlrev_b32_e32 v45, 3, v83

; __device__ __forceinline__ void rwkv_chunk_item(const P& p, const Ctx& c, int seg, int w, bool save) {
;     ...
;     auto gload = [&](int ch, int tidv) { const int t = tidv >> 5, j0 = (tidv & 31) * 2; const size_t go = ((size_t)b * SEGT + ch * 16 + t) * DMIX + hh * 64 + j0;
;         ga = *(const unsigned*)(SA + go); gb = *(const unsigned*)(SB + go); gk = *(const unsigned*)(SK + go); gr = *(const unsigned*)(SR + go); gv = *(const unsigned*)(SV + go);
;         if (tidv < 64) gg = GTB[((size_t)(b * 32 + ch) * 24 + hh) * 64 + tidv]; };
;     ...
;         if (ch + 2 < SEGT / 16) gload(ch + 2, tidv);
.LBB0_932:
	s_andn2_b64 vcc, exec, s[70:71]
	s_cbranch_vccz .LBB0_895
	v_ashrrev_i32_e32 v47, 31, v46
	v_lshl_add_u64 v[46:47], s[76:77], 0, v[46:47]
	v_mov_b64_e32 v[48:49], s[14:15]
	v_mad_u64_u32 v[48:49], s[2:3], v46, s58, v[48:49]
	v_mov_b32_e32 v46, v49
	v_mad_u64_u32 v[46:47], s[2:3], v47, s58, v[46:47]
	v_and_or_b32 v48, v45, 62, v48
	v_mov_b32_e32 v49, v46
	v_lshlrev_b64 v[46:47], 1, v[48:49]
	v_lshl_add_u64 v[48:49], s[16:17], 0, v[46:47]
	global_load_dword v71, v[48:49], off
	v_lshl_add_u64 v[48:49], s[26:27], 0, v[46:47]
	global_load_dword v74, v[48:49], off
	v_lshl_add_u64 v[48:49], s[20:21], 0, v[46:47]
	global_load_dword v75, v[48:49], off
	v_lshl_add_u64 v[48:49], s[30:31], 0, v[46:47]
	v_lshl_add_u64 v[46:47], s[24:25], 0, v[46:47]
	global_load_dword v76, v[48:49], off
	global_load_dword v79, v[46:47], off
	v_cmp_gt_i32_e32 vcc, 64, v44
	s_and_saveexec_b64 s[2:3], vcc
	s_cbranch_execz .LBB0_934
	s_add_i32 s78, s85, s86
	s_mul_hi_i32 s79, s78, 24
	s_mul_i32 s78, s78, 24
	s_add_u32 s78, s78, s46
	s_addc_u32 s79, s79, s47
	s_lshl_b64 s[78:79], s[78:79], 8
	s_add_u32 s78, s81, s78
	v_ashrrev_i32_e32 v45, 31, v44
	s_addc_u32 s79, s82, s79
	v_lshl_add_u64 v[44:45], v[44:45], 2, s[78:79]
	global_load_dword v27, v[44:45], off
